# scan: XCD map + A/F compute trims + staging loads through SGPR bases (fewer VALU)
# baseline (speedup 1.0000x reference)
.LBB0_626:
	s_or_b64 exec, exec, s[0:1]
	v_lshlrev_b32_e32 v4, 16, v67
	v_mul_f32_e32 v4, 0xbfb8aa3b, v4
	v_exp_f32_e32 v4, v4
	s_or_b32 s0, s30, 7
	v_lshlrev_b32_e32 v0, 16, v31
	v_lshlrev_b32_e32 v2, 16, v70
	v_mul_f32_e32 v0, v41, v0
	v_add_f32_e32 v5, -1.0, v2
	s_lshl_b32 s27, s0, 8
	v_mul_f32_e32 v0, v32, v0
	v_fma_f32 v5, v42, v5, 1.0
	s_add_i32 s1, s36, s27
	v_mul_f32_e32 v3, v5, v3
	v_mul_f32_e32 v0, v4, v0
	v_lshl_add_u32 v5, v37, 2, s1
	ds_write2st64_b32 v5, v0, v4 offset1:16
	v_mul_f32_e32 v0, v1, v2
	ds_write2st64_b32 v5, v0, v3 offset0:32 offset1:48
	v_lshlrev_b32_e32 v0, 16, v27
	v_lshlrev_b32_e32 v1, 16, v62
	s_lshl_b32 s25, s0, 3
	ds_write2st64_b32 v5, v0, v1 offset0:64 offset1:80
	s_and_saveexec_b64 s[0:1], s[2:3]
	s_add_i32 s36, s36, s25
	v_mov_b32_e32 v0, v29
	v_mov_b32_e32 v1, v30
	v_mov_b32_e32 v2, s36
	ds_write_b64 v2, v[0:1] offset:24576
	s_or_b64 exec, exec, s[0:1]
	s_or_b32 s0, s31, 16
	v_readlane_b32 s50, v253, 20
	s_add_i32 s48, s0, s50
	v_readlane_b32 s46, v254, 25
	s_lshl_b64 s[36:37], s[48:49], 10
	v_or3_b32 v1, s37, 0, 0
	v_mov_b32_e32 v28, s46
	v_or3_b32 v0, s36, v28, v37
	v_lshlrev_b64 v[0:1], 1, v[0:1]
	v_lshl_add_u64 v[2:3], s[4:5], 0, v[0:1]
	global_load_ushort v43, v[2:3], off
	v_lshl_add_u64 v[2:3], s[8:9], 0, v[0:1]
	s_lshl_b64 s[36:37], s[48:49], 8
	global_load_ushort v45, v[2:3], off
	v_lshl_add_u64 v[2:3], s[10:11], 0, v[0:1]
	s_add_u32 s36, s16, s36
	global_load_ushort v44, v[2:3], off
	v_lshl_add_u64 v[2:3], s[6:7], 0, v[0:1]
	v_lshl_add_u64 v[0:1], s[12:13], 0, v[0:1]
	s_addc_u32 s37, s17, s37
	v_readlane_b32 s47, v254, 26
	global_load_ushort v46, v[2:3], off
	global_load_ushort v49, v[0:1], off
	s_mov_b32 s40, 1
	global_load_dwordx4 v[0:3], v177, s[36:37]
	s_or_b32 s36, s48, 1
	s_mov_b32 s37, s49
	s_lshl_b64 s[46:47], s[36:37], 10
	v_or3_b32 v5, s47, 0, 0
	v_or3_b32 v4, s46, v28, v37
	v_lshlrev_b64 v[4:5], 1, v[4:5]
	v_lshl_add_u64 v[6:7], s[4:5], 0, v[4:5]
	global_load_ushort v3, v[6:7], off
	v_lshl_add_u64 v[6:7], s[8:9], 0, v[4:5]
	s_lshl_b64 s[36:37], s[36:37], 8
	global_load_ushort v52, v[6:7], off
	v_lshl_add_u64 v[6:7], s[10:11], 0, v[4:5]
	s_add_u32 s36, s16, s36
	global_load_ushort v47, v[6:7], off
	v_lshl_add_u64 v[6:7], s[6:7], 0, v[4:5]
	v_lshl_add_u64 v[4:5], s[12:13], 0, v[4:5]
	s_addc_u32 s37, s17, s37
	global_load_ushort v50, v[6:7], off
	global_load_ushort v53, v[4:5], off
	v_lshlrev_b32_e32 v36, 1, v36
	global_load_dwordx4 v[4:7], v177, s[36:37]
	s_or_b32 s36, s48, 2
	s_mov_b32 s37, s49
	s_lshl_b64 s[46:47], s[36:37], 10
	v_or3_b32 v9, s47, 0, 0
	v_or3_b32 v8, s46, v28, v37
	v_lshlrev_b64 v[8:9], 1, v[8:9]
	v_lshl_add_u64 v[10:11], s[4:5], 0, v[8:9]
	global_load_ushort v7, v[10:11], off
	v_lshl_add_u64 v[10:11], s[8:9], 0, v[8:9]
	s_lshl_b64 s[36:37], s[36:37], 8
	global_load_ushort v60, v[10:11], off
	v_lshl_add_u64 v[10:11], s[10:11], 0, v[8:9]
	s_add_u32 s36, s16, s36
	global_load_ushort v48, v[10:11], off
	v_lshl_add_u64 v[10:11], s[6:7], 0, v[8:9]
	v_lshl_add_u64 v[8:9], s[12:13], 0, v[8:9]
	s_addc_u32 s37, s17, s37
	global_load_ushort v51, v[10:11], off
	global_load_ushort v55, v[8:9], off
	s_nop 0
	global_load_dwordx4 v[8:11], v177, s[36:37]
	s_or_b32 s36, s48, 3
	s_mov_b32 s37, s49
	s_lshl_b64 s[46:47], s[36:37], 10
	v_or3_b32 v13, s47, 0, 0
	v_or3_b32 v12, s46, v28, v37
	v_lshlrev_b64 v[12:13], 1, v[12:13]
	v_lshl_add_u64 v[14:15], s[4:5], 0, v[12:13]
	global_load_ushort v11, v[14:15], off
	v_lshl_add_u64 v[14:15], s[8:9], 0, v[12:13]
	s_lshl_b64 s[36:37], s[36:37], 8
	global_load_ushort v64, v[14:15], off
	v_lshl_add_u64 v[14:15], s[10:11], 0, v[12:13]
	s_add_u32 s36, s16, s36
	global_load_ushort v54, v[14:15], off
	v_lshl_add_u64 v[14:15], s[6:7], 0, v[12:13]
	v_lshl_add_u64 v[12:13], s[12:13], 0, v[12:13]
	s_addc_u32 s37, s17, s37
	global_load_ushort v57, v[14:15], off
	global_load_ushort v58, v[12:13], off
	s_nop 0
	global_load_dwordx4 v[12:15], v177, s[36:37]
	s_or_b32 s36, s48, 4
	s_mov_b32 s37, s49
	s_lshl_b64 s[46:47], s[36:37], 10
	v_or3_b32 v17, s47, 0, 0
	v_or3_b32 v16, s46, v28, v37
	v_lshlrev_b64 v[16:17], 1, v[16:17]
	v_lshl_add_u64 v[18:19], s[4:5], 0, v[16:17]
	global_load_ushort v15, v[18:19], off
	v_lshl_add_u64 v[18:19], s[8:9], 0, v[16:17]
	s_lshl_b64 s[36:37], s[36:37], 8
	global_load_ushort v67, v[18:19], off
	v_lshl_add_u64 v[18:19], s[10:11], 0, v[16:17]
	s_add_u32 s36, s16, s36
	global_load_ushort v56, v[18:19], off
	v_lshl_add_u64 v[18:19], s[6:7], 0, v[16:17]
	v_lshl_add_u64 v[16:17], s[12:13], 0, v[16:17]
	s_addc_u32 s37, s17, s37
	global_load_ushort v61, v[18:19], off
	global_load_ushort v63, v[16:17], off
	s_nop 0
	global_load_dwordx4 v[16:19], v177, s[36:37]
	s_or_b32 s36, s48, 5
	s_mov_b32 s37, s49
	s_lshl_b64 s[46:47], s[36:37], 10
	v_or3_b32 v21, s47, 0, 0
	v_or3_b32 v20, s46, v28, v37
	v_lshlrev_b64 v[20:21], 1, v[20:21]
	v_lshl_add_u64 v[22:23], s[4:5], 0, v[20:21]
	global_load_ushort v19, v[22:23], off
	v_lshl_add_u64 v[22:23], s[8:9], 0, v[20:21]
	s_lshl_b64 s[36:37], s[36:37], 8
	global_load_ushort v72, v[22:23], off
	v_lshl_add_u64 v[22:23], s[10:11], 0, v[20:21]
	s_add_u32 s36, s16, s36
	global_load_ushort v59, v[22:23], off
	v_lshl_add_u64 v[22:23], s[6:7], 0, v[20:21]
	v_lshl_add_u64 v[20:21], s[12:13], 0, v[20:21]
	s_addc_u32 s37, s17, s37
	global_load_ushort v62, v[22:23], off
	global_load_ushort v66, v[20:21], off
	s_nop 0
	global_load_dwordx4 v[20:23], v177, s[36:37]
	s_or_b32 s36, s48, 6
	s_mov_b32 s37, s49
	s_lshl_b64 s[46:47], s[36:37], 10
	v_or3_b32 v25, s47, 0, 0
	v_or3_b32 v24, s46, v28, v37
	v_lshlrev_b64 v[24:25], 1, v[24:25]
	v_lshl_add_u64 v[26:27], s[4:5], 0, v[24:25]
	global_load_ushort v23, v[26:27], off
	v_lshl_add_u64 v[26:27], s[8:9], 0, v[24:25]
	s_lshl_b64 s[36:37], s[36:37], 8
	global_load_ushort v74, v[26:27], off
	v_lshl_add_u64 v[26:27], s[10:11], 0, v[24:25]
	s_add_u32 s36, s16, s36
	global_load_ushort v65, v[26:27], off
	v_lshl_add_u64 v[26:27], s[6:7], 0, v[24:25]
	v_lshl_add_u64 v[24:25], s[12:13], 0, v[24:25]
	s_addc_u32 s37, s17, s37
	s_or_b32 s48, s48, 7
	global_load_ushort v69, v[26:27], off
	global_load_ushort v71, v[24:25], off
	s_nop 0
	global_load_dwordx4 v[24:27], v177, s[36:37]
	s_lshl_b64 s[36:37], s[48:49], 10
	v_or3_b32 v29, s37, 0, 0
	v_or3_b32 v28, s36, v28, v37
	s_lshl_b64 s[36:37], s[48:49], 8
	s_add_u32 s36, s16, s36
	s_addc_u32 s37, s17, s37
	s_min_u32 s0, s0, 0x1ff7
	v_lshlrev_b64 v[28:29], 1, v[28:29]
	s_add_i32 s48, s0, s51
	v_lshl_add_u64 v[30:31], s[4:5], 0, v[28:29]
	s_lshl_b64 s[0:1], s[48:49], 11
	global_load_ushort v27, v[30:31], off
	v_lshl_add_u64 v[30:31], s[8:9], 0, v[28:29]
	s_add_u32 s0, s8, s0
	global_load_ushort v75, v[30:31], off
	v_lshl_add_u64 v[30:31], s[10:11], 0, v[28:29]
	s_addc_u32 s1, s9, s1
	global_load_ushort v68, v[30:31], off
	v_lshl_add_u64 v[30:31], s[6:7], 0, v[28:29]
	v_lshl_add_u64 v[28:29], s[12:13], 0, v[28:29]
	s_add_u32 s0, s0, s33
	global_load_ushort v70, v[30:31], off
	global_load_ushort v73, v[28:29], off
	s_addc_u32 s1, s1, 0
	global_load_dwordx4 v[28:31], v177, s[36:37]
	global_load_ushort v31, v176, s[0:1]
	s_lshl_b64 s[0:1], s[48:49], 8
	s_add_u32 s0, s16, s0
	s_addc_u32 s1, s17, s1
	global_load_dwordx4 v[32:35], v177, s[0:1]
	s_waitcnt lgkmcnt(0)
	s_barrier
	s_add_u32 s0, s8, s33
	s_addc_u32 s1, s9, 0
	s_add_i32 s29, s29, s30
	v_lshl_add_u64 v[38:39], s[0:1], 0, v[176:177]
	s_lshl_b32 s37, s28, 6
	s_lshl_b32 s36, s34, 3
	s_lshl_b32 s35, s35, 3
	s_lshl_b32 s34, s41, 3
	s_lshl_b32 s33, s42, 3
	s_lshl_b32 s31, s44, 3
	s_lshl_b32 s28, s45, 3
	s_add_i32 s30, s29, s50
	s_mov_b32 s41, 0
	s_add_i32 s1, s30, s41
	s_add_i32 s48, s1, 32
	s_lshl_b64 s[44:45], s[48:49], 11
	v_or_b32_e32 v100, s44, v36
	s_add_i32 s0, s29, s41
	s_add_i32 s0, s0, 32
	global_load_ushort v143, v100, s[4:5]
	s_lshl_b64 s[44:45], s[48:49], 8
	global_load_ushort v145, v100, s[8:9]
	s_add_u32 s44, s16, s44
	global_load_ushort v144, v100, s[10:11]
	s_addc_u32 s45, s17, s45
	s_add_i32 s48, s1, 33
	global_load_ushort v146, v100, s[6:7]
	global_load_ushort v149, v100, s[12:13]
	s_nop 0
	global_load_dwordx4 v[100:103], v177, s[44:45]
	s_lshl_b64 s[44:45], s[48:49], 11
	v_or_b32_e32 v104, s44, v36
	global_load_ushort v103, v104, s[4:5]
	s_lshl_b64 s[44:45], s[48:49], 8
	global_load_ushort v152, v104, s[8:9]
	s_add_u32 s44, s16, s44
	global_load_ushort v147, v104, s[10:11]
	s_addc_u32 s45, s17, s45
	s_add_i32 s48, s1, 34
	global_load_ushort v150, v104, s[6:7]
	global_load_ushort v153, v104, s[12:13]
	s_nop 0
	global_load_dwordx4 v[104:107], v177, s[44:45]
	s_lshl_b64 s[44:45], s[48:49], 11
	v_or_b32_e32 v108, s44, v36
	global_load_ushort v107, v108, s[4:5]
	s_lshl_b64 s[44:45], s[48:49], 8
	global_load_ushort v160, v108, s[8:9]
	s_add_u32 s44, s16, s44
	global_load_ushort v148, v108, s[10:11]
	s_addc_u32 s45, s17, s45
	s_add_i32 s48, s1, 35
	global_load_ushort v151, v108, s[6:7]
	global_load_ushort v155, v108, s[12:13]
	s_nop 0
	global_load_dwordx4 v[108:111], v177, s[44:45]
	s_lshl_b64 s[44:45], s[48:49], 11
	v_or_b32_e32 v112, s44, v36
	global_load_ushort v111, v112, s[4:5]
	s_lshl_b64 s[44:45], s[48:49], 8
	global_load_ushort v164, v112, s[8:9]
	s_add_u32 s44, s16, s44
	global_load_ushort v154, v112, s[10:11]
	s_addc_u32 s45, s17, s45
	s_add_i32 s48, s1, 36
	global_load_ushort v157, v112, s[6:7]
	global_load_ushort v158, v112, s[12:13]
	s_nop 0
	global_load_dwordx4 v[112:115], v177, s[44:45]
	s_lshl_b64 s[44:45], s[48:49], 11
	v_or_b32_e32 v116, s44, v36
	global_load_ushort v115, v116, s[4:5]
	s_lshl_b64 s[44:45], s[48:49], 8
	global_load_ushort v167, v116, s[8:9]
	s_add_u32 s44, s16, s44
	global_load_ushort v156, v116, s[10:11]
	s_addc_u32 s45, s17, s45
	s_add_i32 s48, s1, 37
	global_load_ushort v161, v116, s[6:7]
	global_load_ushort v163, v116, s[12:13]
	s_nop 0
	global_load_dwordx4 v[116:119], v177, s[44:45]
	s_lshl_b64 s[44:45], s[48:49], 11
	v_or_b32_e32 v120, s44, v36
	global_load_ushort v119, v120, s[4:5]
	s_lshl_b64 s[44:45], s[48:49], 8
	global_load_ushort v172, v120, s[8:9]
	s_add_u32 s44, s16, s44
	global_load_ushort v159, v120, s[10:11]
	s_addc_u32 s45, s17, s45
	s_add_i32 s48, s1, 38
	global_load_ushort v162, v120, s[6:7]
	global_load_ushort v166, v120, s[12:13]
	s_nop 0
	global_load_dwordx4 v[120:123], v177, s[44:45]
	s_lshl_b64 s[44:45], s[48:49], 11
	v_or_b32_e32 v124, s44, v36
	global_load_ushort v123, v124, s[4:5]
	s_lshl_b64 s[44:45], s[48:49], 8
	global_load_ushort v174, v124, s[8:9]
	s_add_u32 s44, s16, s44
	global_load_ushort v165, v124, s[10:11]
	s_addc_u32 s45, s17, s45
	s_add_i32 s48, s1, 39
	global_load_ushort v169, v124, s[6:7]
	global_load_ushort v171, v124, s[12:13]
	s_nop 0
	global_load_dwordx4 v[124:127], v177, s[44:45]
	s_lshl_b64 s[44:45], s[48:49], 11
	v_or_b32_e32 v128, s44, v36
	s_lshl_b64 s[44:45], s[48:49], 8
	s_add_u32 s44, s16, s44
	s_addc_u32 s45, s17, s45
	s_min_i32 s0, s0, 0x1ff7
	s_add_i32 s48, s0, s51
	global_load_ushort v127, v128, s[4:5]
	s_lshl_b64 s[0:1], s[48:49], 11
	global_load_ushort v175, v128, s[8:9]
	v_lshl_add_u64 v[132:133], v[38:39], 0, s[0:1]
	s_lshl_b64 s[0:1], s[48:49], 8
	global_load_ushort v168, v128, s[10:11]
	s_add_u32 s0, s16, s0
	global_load_ushort v170, v128, s[6:7]
	global_load_ushort v173, v128, s[12:13]
	s_addc_u32 s1, s17, s1
	global_load_dwordx4 v[128:131], v177, s[44:45]
	global_load_ushort v131, v[132:133], off
	global_load_dwordx4 v[132:135], v177, s[0:1]
	s_branch .LBB0_630
.LBB0_629:
	s_or_b64 exec, exec, s[0:1]
	s_add_i32 s1, s30, s41
	s_add_i32 s48, s1, 48
	s_lshl_b64 s[44:45], s[48:49], 11
	v_or_b32_e32 v0, s44, v36
	s_add_i32 s0, s29, s41
	s_add_i32 s0, s0, 48
	global_load_ushort v43, v0, s[4:5]
	s_lshl_b64 s[44:45], s[48:49], 8
	global_load_ushort v45, v0, s[8:9]
	s_add_u32 s44, s16, s44
	global_load_ushort v44, v0, s[10:11]
	s_addc_u32 s45, s17, s45
	s_add_i32 s48, s1, 49
	global_load_ushort v46, v0, s[6:7]
	global_load_ushort v49, v0, s[12:13]
	s_nop 0
	global_load_dwordx4 v[0:3], v177, s[44:45]
	s_lshl_b64 s[44:45], s[48:49], 11
	v_or_b32_e32 v4, s44, v36
	global_load_ushort v3, v4, s[4:5]
	s_lshl_b64 s[44:45], s[48:49], 8
	global_load_ushort v52, v4, s[8:9]
	s_add_u32 s44, s16, s44
	global_load_ushort v47, v4, s[10:11]
	s_addc_u32 s45, s17, s45
	s_add_i32 s48, s1, 50
	global_load_ushort v50, v4, s[6:7]
	global_load_ushort v53, v4, s[12:13]
	s_nop 0
	global_load_dwordx4 v[4:7], v177, s[44:45]
	s_lshl_b64 s[44:45], s[48:49], 11
	v_or_b32_e32 v8, s44, v36
	global_load_ushort v7, v8, s[4:5]
	s_lshl_b64 s[44:45], s[48:49], 8
	global_load_ushort v60, v8, s[8:9]
	s_add_u32 s44, s16, s44
	global_load_ushort v48, v8, s[10:11]
	s_addc_u32 s45, s17, s45
	s_add_i32 s48, s1, 51
	global_load_ushort v51, v8, s[6:7]
	global_load_ushort v55, v8, s[12:13]
	s_nop 0
	global_load_dwordx4 v[8:11], v177, s[44:45]
	s_lshl_b64 s[44:45], s[48:49], 11
	v_or_b32_e32 v12, s44, v36
	global_load_ushort v11, v12, s[4:5]
	s_lshl_b64 s[44:45], s[48:49], 8
	global_load_ushort v64, v12, s[8:9]
	s_add_u32 s44, s16, s44
	global_load_ushort v54, v12, s[10:11]
	s_addc_u32 s45, s17, s45
	s_add_i32 s48, s1, 52
	global_load_ushort v57, v12, s[6:7]
	global_load_ushort v58, v12, s[12:13]
	s_nop 0
	global_load_dwordx4 v[12:15], v177, s[44:45]
	s_lshl_b64 s[44:45], s[48:49], 11
	v_or_b32_e32 v16, s44, v36
	global_load_ushort v15, v16, s[4:5]
	s_lshl_b64 s[44:45], s[48:49], 8
	global_load_ushort v67, v16, s[8:9]
	s_add_u32 s44, s16, s44
	global_load_ushort v56, v16, s[10:11]
	s_addc_u32 s45, s17, s45
	s_add_i32 s48, s1, 53
	global_load_ushort v61, v16, s[6:7]
	global_load_ushort v63, v16, s[12:13]
	s_nop 0
	global_load_dwordx4 v[16:19], v177, s[44:45]
	s_lshl_b64 s[44:45], s[48:49], 11
	v_or_b32_e32 v20, s44, v36
	global_load_ushort v19, v20, s[4:5]
	s_lshl_b64 s[44:45], s[48:49], 8
	global_load_ushort v72, v20, s[8:9]
	s_add_u32 s44, s16, s44
	global_load_ushort v59, v20, s[10:11]
	s_addc_u32 s45, s17, s45
	s_add_i32 s48, s1, 54
	global_load_ushort v62, v20, s[6:7]
	global_load_ushort v66, v20, s[12:13]
	s_nop 0
	global_load_dwordx4 v[20:23], v177, s[44:45]
	s_lshl_b64 s[44:45], s[48:49], 11
	v_or_b32_e32 v24, s44, v36
	global_load_ushort v23, v24, s[4:5]
	s_lshl_b64 s[44:45], s[48:49], 8
	global_load_ushort v74, v24, s[8:9]
	s_add_u32 s44, s16, s44
	global_load_ushort v65, v24, s[10:11]
	s_addc_u32 s45, s17, s45
	s_add_i32 s48, s1, 55
	global_load_ushort v69, v24, s[6:7]
	global_load_ushort v71, v24, s[12:13]
	s_nop 0
	global_load_dwordx4 v[24:27], v177, s[44:45]
	s_lshl_b64 s[44:45], s[48:49], 11
	v_or_b32_e32 v28, s44, v36
	s_lshl_b64 s[44:45], s[48:49], 8
	s_add_u32 s44, s16, s44
	s_addc_u32 s45, s17, s45
	s_min_i32 s0, s0, 0x1ff7
	s_add_i32 s48, s0, s51
	global_load_ushort v27, v28, s[4:5]
	s_lshl_b64 s[0:1], s[48:49], 11
	global_load_ushort v75, v28, s[8:9]
	v_lshl_add_u64 v[32:33], v[38:39], 0, s[0:1]
	s_lshl_b64 s[0:1], s[48:49], 8
	global_load_ushort v68, v28, s[10:11]
	s_add_u32 s0, s16, s0
	global_load_ushort v70, v28, s[6:7]
	global_load_ushort v73, v28, s[12:13]
	s_addc_u32 s1, s17, s1
	global_load_dwordx4 v[28:31], v177, s[44:45]
	global_load_ushort v31, v[32:33], off
	s_add_i32 s41, s41, 16
	global_load_dwordx4 v[32:35], v177, s[0:1]
	s_waitcnt lgkmcnt(0)
	s_barrier
	s_add_i32 s40, s40, 1
	s_cmpk_eq_i32 s41, 0xfe0
	s_cbranch_scc1 .LBB0_646
	s_waitcnt vmcnt(50)
	v_lshlrev_b32_e32 v134, 16, v149
	s_and_b32 s0, s40, 1
	v_lshlrev_b32_e32 v133, 16, v145
	v_lshlrev_b32_e32 v135, 16, v146
	v_add_f32_e32 v145, -1.0, v134
	s_or_b32 s0, s0, s20
	v_mul_f32_e32 v135, 0xbfb8aa3b, v135
	v_fma_f32 v145, v42, v145, 1.0
	s_mulk_i32 s0, 0x6080
	v_exp_f32_e32 v135, v135
	v_mul_f32_e32 v145, v145, v133
	v_mul_f32_e32 v133, v41, v133
	s_add_i32 s42, s0, 0
	v_mul_f32_e32 v100, v100, v133
	v_lshlrev_b32_e32 v133, 16, v152
	v_mul_f32_e32 v146, v41, v133
	s_add_i32 s0, s42, s18
	v_mul_f32_e32 v104, v146, v104
	v_lshl_add_u32 v149, v37, 2, s0
	v_mul_f32_e32 v100, v100, v134
	v_mul_f32_e32 v146, v104, v135
	ds_write2st64_b32 v149, v100, v145 offset0:32 offset1:48
	v_lshlrev_b32_e32 v100, 16, v143
	v_lshlrev_b32_e32 v134, 16, v144
	ds_write2st64_b32 v149, v146, v135 offset1:16
	ds_write2st64_b32 v149, v100, v134 offset0:64 offset1:80
	s_and_saveexec_b64 s[0:1], s[2:3]
	s_add_i32 s44, s42, s37
	v_mov_b32_e32 v100, v101
	v_mov_b32_e32 v101, v102
	v_mov_b32_e32 v102, s44
	ds_write_b64 v102, v[100:101] offset:24576
	s_or_b64 exec, exec, s[0:1]
	v_lshlrev_b32_e32 v102, 16, v160
	v_mul_f32_e32 v100, v41, v102
	v_mul_f32_e32 v100, v100, v108
	v_lshlrev_b32_e32 v108, 16, v150
	v_mul_f32_e32 v108, 0xbfb8aa3b, v108
	v_lshlrev_b32_e32 v101, 16, v153
	v_exp_f32_e32 v108, v108
	v_add_f32_e32 v134, -1.0, v101
	v_fma_f32 v134, v42, v134, 1.0
	s_add_i32 s0, s42, s19
	v_mul_f32_e32 v133, v134, v133
	v_lshl_add_u32 v135, v37, 2, s0
	v_mul_f32_e32 v101, v104, v101
	v_mul_f32_e32 v134, v100, v108
	ds_write2st64_b32 v135, v101, v133 offset0:32 offset1:48
	v_lshlrev_b32_e32 v101, 16, v103
	v_lshlrev_b32_e32 v103, 16, v147
	ds_write2st64_b32 v135, v134, v108 offset1:16
	ds_write2st64_b32 v135, v101, v103 offset0:64 offset1:80
	s_and_saveexec_b64 s[0:1], s[2:3]
	s_add_i32 s44, s42, s36
	v_mov_b32_e32 v104, v105
	v_mov_b32_e32 v105, v106
	v_mov_b32_e32 v101, s44
	ds_write_b64 v101, v[104:105] offset:24576
	s_or_b64 exec, exec, s[0:1]
	v_lshlrev_b32_e32 v105, 16, v151
	v_mul_f32_e32 v105, 0xbfb8aa3b, v105
	v_lshlrev_b32_e32 v104, 16, v155
	v_exp_f32_e32 v105, v105
	v_lshlrev_b32_e32 v103, 16, v164
	v_add_f32_e32 v106, -1.0, v104
	v_mul_f32_e32 v101, v41, v103
	v_fma_f32 v106, v42, v106, 1.0
	s_add_i32 s0, s42, s21
	v_mul_f32_e32 v101, v101, v112
	v_mul_f32_e32 v102, v106, v102
	v_lshl_add_u32 v108, v37, 2, s0
	v_mul_f32_e32 v100, v100, v104
	v_mul_f32_e32 v106, v101, v105
	ds_write2st64_b32 v108, v100, v102 offset0:32 offset1:48
	v_lshlrev_b32_e32 v100, 16, v107
	v_lshlrev_b32_e32 v102, 16, v148
	ds_write2st64_b32 v108, v106, v105 offset1:16
	ds_write2st64_b32 v108, v100, v102 offset0:64 offset1:80
	s_and_saveexec_b64 s[0:1], s[2:3]
	s_add_i32 s44, s42, s35
	v_mov_b32_e32 v104, v109
	v_mov_b32_e32 v105, v110
	v_mov_b32_e32 v100, s44
	ds_write_b64 v100, v[104:105] offset:24576
	s_or_b64 exec, exec, s[0:1]
	v_lshlrev_b32_e32 v105, 16, v157
	v_mul_f32_e32 v105, 0xbfb8aa3b, v105
	v_lshlrev_b32_e32 v104, 16, v158
	v_exp_f32_e32 v105, v105
	v_lshlrev_b32_e32 v102, 16, v167
	v_add_f32_e32 v106, -1.0, v104
	v_mul_f32_e32 v100, v41, v102
	v_fma_f32 v106, v42, v106, 1.0
	s_add_i32 s0, s42, s22
	v_mul_f32_e32 v100, v100, v116
	v_mul_f32_e32 v103, v106, v103
	v_lshl_add_u32 v107, v37, 2, s0
	v_mul_f32_e32 v101, v101, v104
	v_mul_f32_e32 v106, v100, v105
	ds_write2st64_b32 v107, v101, v103 offset0:32 offset1:48
	v_lshlrev_b32_e32 v101, 16, v111
	v_lshlrev_b32_e32 v103, 16, v154
	ds_write2st64_b32 v107, v106, v105 offset1:16
	ds_write2st64_b32 v107, v101, v103 offset0:64 offset1:80
	s_and_saveexec_b64 s[0:1], s[2:3]
	s_add_i32 s44, s42, s34
	v_mov_b32_e32 v104, v113
	v_mov_b32_e32 v105, v114
	v_mov_b32_e32 v101, s44
	ds_write_b64 v101, v[104:105] offset:24576
	s_or_b64 exec, exec, s[0:1]
	v_lshlrev_b32_e32 v105, 16, v161
	v_mul_f32_e32 v105, 0xbfb8aa3b, v105
	v_lshlrev_b32_e32 v104, 16, v163
	v_exp_f32_e32 v105, v105
	v_lshlrev_b32_e32 v103, 16, v172
	v_add_f32_e32 v106, -1.0, v104
	v_mul_f32_e32 v101, v41, v103
	v_fma_f32 v106, v42, v106, 1.0
	s_add_i32 s0, s42, s23
	v_mul_f32_e32 v101, v101, v120
	v_mul_f32_e32 v102, v106, v102
	v_lshl_add_u32 v107, v37, 2, s0
	v_mul_f32_e32 v100, v100, v104
	v_mul_f32_e32 v106, v101, v105
	ds_write2st64_b32 v107, v100, v102 offset0:32 offset1:48
	v_lshlrev_b32_e32 v100, 16, v115
	v_lshlrev_b32_e32 v102, 16, v156
	ds_write2st64_b32 v107, v106, v105 offset1:16
	ds_write2st64_b32 v107, v100, v102 offset0:64 offset1:80
	s_and_saveexec_b64 s[0:1], s[2:3]
	s_add_i32 s44, s42, s33
	v_mov_b32_e32 v104, v117
	v_mov_b32_e32 v105, v118
	v_mov_b32_e32 v100, s44
	ds_write_b64 v100, v[104:105] offset:24576
	s_or_b64 exec, exec, s[0:1]
	v_lshlrev_b32_e32 v105, 16, v162
	v_mul_f32_e32 v105, 0xbfb8aa3b, v105
	v_lshlrev_b32_e32 v104, 16, v166
	v_exp_f32_e32 v105, v105
	v_lshlrev_b32_e32 v102, 16, v174
	v_add_f32_e32 v106, -1.0, v104
	v_mul_f32_e32 v100, v41, v102
	v_fma_f32 v106, v42, v106, 1.0
	s_add_i32 s0, s42, s24
	v_mul_f32_e32 v100, v100, v124
	v_mul_f32_e32 v103, v106, v103
	v_lshl_add_u32 v107, v37, 2, s0
	v_mul_f32_e32 v101, v101, v104
	v_mul_f32_e32 v106, v100, v105
	ds_write2st64_b32 v107, v101, v103 offset0:32 offset1:48
	v_lshlrev_b32_e32 v101, 16, v119
	v_lshlrev_b32_e32 v103, 16, v159
	ds_write2st64_b32 v107, v106, v105 offset1:16
	ds_write2st64_b32 v107, v101, v103 offset0:64 offset1:80
	s_and_saveexec_b64 s[0:1], s[2:3]
	s_add_i32 s44, s42, s31
	v_mov_b32_e32 v104, v121
	v_mov_b32_e32 v105, v122
	v_mov_b32_e32 v101, s44
	ds_write_b64 v101, v[104:105] offset:24576
	s_or_b64 exec, exec, s[0:1]
	v_lshlrev_b32_e32 v105, 16, v169
	v_mul_f32_e32 v105, 0xbfb8aa3b, v105
	v_lshlrev_b32_e32 v104, 16, v171
	v_exp_f32_e32 v105, v105
	v_lshlrev_b32_e32 v103, 16, v175
	v_add_f32_e32 v106, -1.0, v104
	v_mul_f32_e32 v101, v41, v103
	v_fma_f32 v106, v42, v106, 1.0
	s_add_i32 s0, s42, s26
	v_mul_f32_e32 v101, v101, v128
	v_mul_f32_e32 v102, v106, v102
	v_lshl_add_u32 v107, v37, 2, s0
	v_mul_f32_e32 v100, v100, v104
	v_mul_f32_e32 v106, v101, v105
	ds_write2st64_b32 v107, v100, v102 offset0:32 offset1:48
	v_lshlrev_b32_e32 v100, 16, v123
	v_lshlrev_b32_e32 v102, 16, v165
	ds_write2st64_b32 v107, v106, v105 offset1:16
	ds_write2st64_b32 v107, v100, v102 offset0:64 offset1:80
	s_and_saveexec_b64 s[0:1], s[2:3]
	s_add_i32 s44, s42, s28
	v_mov_b32_e32 v104, v125
	v_mov_b32_e32 v105, v126
	v_mov_b32_e32 v100, s44
	ds_write_b64 v100, v[104:105] offset:24576
	s_or_b64 exec, exec, s[0:1]
	v_lshlrev_b32_e32 v104, 16, v170
	v_mul_f32_e32 v104, 0xbfb8aa3b, v104
	v_exp_f32_e32 v104, v104
	v_lshlrev_b32_e32 v100, 16, v131
	v_lshlrev_b32_e32 v102, 16, v173
	v_mul_f32_e32 v100, v41, v100
	v_add_f32_e32 v105, -1.0, v102
	v_mul_f32_e32 v100, v100, v132
	v_fma_f32 v105, v42, v105, 1.0
	s_add_i32 s0, s42, s27
	v_mul_f32_e32 v103, v105, v103
	v_mul_f32_e32 v100, v100, v104
	v_lshl_add_u32 v105, v37, 2, s0
	ds_write2st64_b32 v105, v100, v104 offset1:16
	v_mul_f32_e32 v100, v101, v102
	ds_write2st64_b32 v105, v100, v103 offset0:32 offset1:48
	v_lshlrev_b32_e32 v100, 16, v127
	v_lshlrev_b32_e32 v101, 16, v168
	ds_write2st64_b32 v105, v100, v101 offset0:64 offset1:80
	s_and_saveexec_b64 s[0:1], s[2:3]
	s_cbranch_execz .Lst_B_load
	s_add_i32 s42, s42, s25
	v_mov_b32_e32 v100, v129
	v_mov_b32_e32 v101, v130
	v_mov_b32_e32 v102, s42
	ds_write_b64 v102, v[100:101] offset:24576
	s_branch .Lst_B_load
.Lst_B_load:
	s_or_b64 exec, exec, s[0:1]
	s_add_i32 s1, s30, s41
	s_add_i32 s48, s1, 48
	s_lshl_b64 s[44:45], s[48:49], 11
	v_or_b32_e32 v100, s44, v36
	s_add_i32 s0, s29, s41
	s_add_i32 s0, s0, 48
	global_load_ushort v143, v100, s[4:5]
	s_lshl_b64 s[44:45], s[48:49], 8
	global_load_ushort v145, v100, s[8:9]
	s_add_u32 s44, s16, s44
	global_load_ushort v144, v100, s[10:11]
	s_addc_u32 s45, s17, s45
	s_add_i32 s48, s1, 49
	global_load_ushort v146, v100, s[6:7]
	global_load_ushort v149, v100, s[12:13]
	s_nop 0
	global_load_dwordx4 v[100:103], v177, s[44:45]
	s_lshl_b64 s[44:45], s[48:49], 11
	v_or_b32_e32 v104, s44, v36
	global_load_ushort v103, v104, s[4:5]
	s_lshl_b64 s[44:45], s[48:49], 8
	global_load_ushort v152, v104, s[8:9]
	s_add_u32 s44, s16, s44
	global_load_ushort v147, v104, s[10:11]
	s_addc_u32 s45, s17, s45
	s_add_i32 s48, s1, 50
	global_load_ushort v150, v104, s[6:7]
	global_load_ushort v153, v104, s[12:13]
	s_nop 0
	global_load_dwordx4 v[104:107], v177, s[44:45]
	s_lshl_b64 s[44:45], s[48:49], 11
	v_or_b32_e32 v108, s44, v36
	global_load_ushort v107, v108, s[4:5]
	s_lshl_b64 s[44:45], s[48:49], 8
	global_load_ushort v160, v108, s[8:9]
	s_add_u32 s44, s16, s44
	global_load_ushort v148, v108, s[10:11]
	s_addc_u32 s45, s17, s45
	s_add_i32 s48, s1, 51
	global_load_ushort v151, v108, s[6:7]
	global_load_ushort v155, v108, s[12:13]
	s_nop 0
	global_load_dwordx4 v[108:111], v177, s[44:45]
	s_lshl_b64 s[44:45], s[48:49], 11
	v_or_b32_e32 v112, s44, v36
	global_load_ushort v111, v112, s[4:5]
	s_lshl_b64 s[44:45], s[48:49], 8
	global_load_ushort v164, v112, s[8:9]
	s_add_u32 s44, s16, s44
	global_load_ushort v154, v112, s[10:11]
	s_addc_u32 s45, s17, s45
	s_add_i32 s48, s1, 52
	global_load_ushort v157, v112, s[6:7]
	global_load_ushort v158, v112, s[12:13]
	s_nop 0
	global_load_dwordx4 v[112:115], v177, s[44:45]
	s_lshl_b64 s[44:45], s[48:49], 11
	v_or_b32_e32 v116, s44, v36
	global_load_ushort v115, v116, s[4:5]
	s_lshl_b64 s[44:45], s[48:49], 8
	global_load_ushort v167, v116, s[8:9]
	s_add_u32 s44, s16, s44
	global_load_ushort v156, v116, s[10:11]
	s_addc_u32 s45, s17, s45
	s_add_i32 s48, s1, 53
	global_load_ushort v161, v116, s[6:7]
	global_load_ushort v163, v116, s[12:13]
	s_nop 0
	global_load_dwordx4 v[116:119], v177, s[44:45]
	s_lshl_b64 s[44:45], s[48:49], 11
	v_or_b32_e32 v120, s44, v36
	global_load_ushort v119, v120, s[4:5]
	s_lshl_b64 s[44:45], s[48:49], 8
	global_load_ushort v172, v120, s[8:9]
	s_add_u32 s44, s16, s44
	global_load_ushort v159, v120, s[10:11]
	s_addc_u32 s45, s17, s45
	s_add_i32 s48, s1, 54
	global_load_ushort v162, v120, s[6:7]
	global_load_ushort v166, v120, s[12:13]
	s_nop 0
	global_load_dwordx4 v[120:123], v177, s[44:45]
	s_lshl_b64 s[44:45], s[48:49], 11
	v_or_b32_e32 v124, s44, v36
	global_load_ushort v123, v124, s[4:5]
	s_lshl_b64 s[44:45], s[48:49], 8
	global_load_ushort v174, v124, s[8:9]
	s_add_u32 s44, s16, s44
	global_load_ushort v165, v124, s[10:11]
	s_addc_u32 s45, s17, s45
	s_add_i32 s48, s1, 55
	global_load_ushort v169, v124, s[6:7]
	global_load_ushort v171, v124, s[12:13]
	s_nop 0
	global_load_dwordx4 v[124:127], v177, s[44:45]
	s_lshl_b64 s[44:45], s[48:49], 11
	v_or_b32_e32 v128, s44, v36
	s_lshl_b64 s[44:45], s[48:49], 8
	s_add_u32 s44, s16, s44
	s_addc_u32 s45, s17, s45
	s_min_i32 s0, s0, 0x1ff7
	s_add_i32 s48, s0, s51
	global_load_ushort v127, v128, s[4:5]
	s_lshl_b64 s[0:1], s[48:49], 11
	global_load_ushort v175, v128, s[8:9]
	v_lshl_add_u64 v[132:133], v[38:39], 0, s[0:1]
	s_lshl_b64 s[0:1], s[48:49], 8
	global_load_ushort v168, v128, s[10:11]
	s_add_u32 s0, s16, s0
	global_load_ushort v170, v128, s[6:7]
	global_load_ushort v173, v128, s[12:13]
	s_addc_u32 s1, s17, s1
	global_load_dwordx4 v[128:131], v177, s[44:45]
	global_load_ushort v131, v[132:133], off
	s_add_i32 s41, s41, 16
	global_load_dwordx4 v[132:135], v177, s[0:1]
	s_waitcnt lgkmcnt(0)
	s_barrier
	s_add_i32 s40, s40, 1
	s_cmpk_eq_i32 s41, 0xfe0
	s_cbranch_scc1 .LBB0_646
